# attention step: redundant lgkmcnt ladder at loop head collapsed, canonicalising v_max triples and +0 adds removed (bit-identical)
# speedup vs baseline: 1.0082x; 1.0063x over previous
.LBB0_264:
	s_waitcnt lgkmcnt(0)
	v_mfma_f32_32x32x16_bf16 v[144:159], v[220:223], v[184:187], v[80:95]
	v_add_f32_e32 v2, v112, v113
	v_add_f32_e32 v2, v114, v2
	v_add_f32_e32 v2, v115, v2
	s_lshl_b32 s2, s2, 1
	v_add_f32_e32 v2, v116, v2
	v_add_u32_e32 v0, s2, v233
	v_add_f32_e32 v2, v117, v2
	v_cvt_pk_bf16_f32 v188, v112, v113
	v_cvt_pk_bf16_f32 v189, v114, v115
	v_mfma_f32_32x32x16_bf16 v[128:143], v[216:219], v[184:187], v[80:95]
	v_add_f32_e32 v2, v118, v2
	v_add_f32_e32 v2, v119, v2
	v_add_f32_e32 v2, v120, v2
	v_add_f32_e32 v2, v121, v2
	v_cvt_pk_bf16_f32 v190, v116, v117
	v_cvt_pk_bf16_f32 v191, v118, v119
	v_mfma_f32_32x32x16_bf16 v[144:159], v[212:215], v[176:179], v[144:159]
	v_add_f32_e32 v2, v122, v2
	v_add_f32_e32 v2, v123, v2
	v_add_f32_e32 v2, v124, v2
	v_add_f32_e32 v2, v125, v2
	v_cvt_pk_bf16_f32 v180, v120, v121
	v_cvt_pk_bf16_f32 v181, v122, v123
	v_mfma_f32_32x32x16_bf16 v[128:143], v[208:211], v[176:179], v[128:143]
	v_add_f32_e32 v2, v126, v2
	v_add_f32_e32 v2, v127, v2
	v_add_f32_e32 v2, v96, v2
	v_add_f32_e32 v2, v97, v2
	v_cvt_pk_bf16_f32 v182, v124, v125
	v_cvt_pk_bf16_f32 v183, v126, v127
	v_mfma_f32_32x32x16_bf16 v[144:159], v[204:207], v[172:175], v[144:159]
	v_add_f32_e32 v2, v98, v2
	v_add_f32_e32 v2, v99, v2
	v_add_f32_e32 v2, v100, v2
	v_add_f32_e32 v2, v101, v2
	v_cvt_pk_bf16_f32 v168, v96, v97
	v_cvt_pk_bf16_f32 v169, v98, v99
	v_mfma_f32_32x32x16_bf16 v[128:143], v[200:203], v[172:175], v[128:143]
	v_add_f32_e32 v2, v102, v2
	v_add_f32_e32 v2, v103, v2
	v_add_f32_e32 v2, v104, v2
	v_add_f32_e32 v2, v105, v2
	v_cvt_pk_bf16_f32 v170, v100, v101
	v_cvt_pk_bf16_f32 v171, v102, v103
	v_mfma_f32_32x32x16_bf16 v[144:159], v[196:199], v[164:167], v[144:159]
	v_add_f32_e32 v2, v106, v2
	v_add_f32_e32 v2, v107, v2
	v_add_f32_e32 v2, v108, v2
	v_add_f32_e32 v2, v109, v2
	v_cvt_pk_bf16_f32 v160, v104, v105
	v_cvt_pk_bf16_f32 v161, v106, v107
	v_mfma_f32_32x32x16_bf16 v[128:143], v[192:195], v[164:167], v[128:143]
	v_add_f32_e32 v2, v110, v2
	v_add_f32_e32 v102, v111, v2
	v_cvt_pk_bf16_f32 v162, v108, v109
	v_cvt_pk_bf16_f32 v163, v110, v111
	ds_read_b64_tr_b16 v[96:97], v0 offset:24576
	ds_read_b64_tr_b16 v[98:99], v0 offset:25088
	ds_read_b64_tr_b16 v[10:11], v0 offset:28672
	ds_read_b64_tr_b16 v[12:13], v0 offset:29184
	ds_read_b64_tr_b16 v[6:7], v0 offset:32768
	ds_read_b64_tr_b16 v[8:9], v0 offset:33280
	ds_read_b64_tr_b16 v[2:3], v0 offset:36864
	ds_read_b64_tr_b16 v[4:5], v0 offset:37376
	v_lshl_add_u64 v[208:209], v[238:239], 0, s[54:55]
	v_lshl_add_u64 v[14:15], v[208:209], 0, s[74:75]
	s_add_i32 s2, s4, s22
	s_mov_b32 m0, s2
	s_nop 0
	global_load_lds_dwordx4 v[14:15], off
	v_lshl_add_u64 v[14:15], v[242:243], 0, s[54:55]
	v_lshl_add_u64 v[100:101], v[14:15], 0, s[66:67]
	s_lshl_b32 s2, s96, 1
	s_add_i32 s2, s2, s23
	s_mov_b32 m0, s2
	s_nop 0
	global_load_lds_dwordx4 v[100:101], off
	v_lshl_add_u64 v[100:101], v[14:15], 0, s[84:85]
	s_addk_i32 s2, 0x2000
	s_mov_b32 m0, s2
	s_nop 0
	global_load_lds_dwordx4 v[100:101], off
	v_max_f32_e32 v100, v144, v145
	v_max3_f32 v101, v146, v147, v129
	v_max3_f32 v100, v100, v128, v130
	v_max3_f32 v100, v100, v131, v148
	v_max3_f32 v101, v101, v150, v151
	v_max3_f32 v100, v100, v149, v132
	v_max3_f32 v101, v101, v134, v135
	v_max3_f32 v100, v100, v133, v152
	v_max3_f32 v101, v101, v154, v155
	v_max3_f32 v100, v100, v153, v136
	v_max3_f32 v101, v101, v138, v139
	v_max3_f32 v100, v100, v137, v156
	v_max3_f32 v101, v101, v158, v159
	v_max3_f32 v100, v100, v157, v140
	v_max3_f32 v101, v101, v142, v143
	v_max3_f32 v100, v100, v141, v101
	v_mov_b32_e32 v101, v100
	s_nop 1
	v_permlane32_swap_b32_e32 v100, v101
	v_max_f32_e32 v100, v100, v101
	v_cmp_lt_f32_e32 vcc, s11, v100
	s_cmp_lg_u64 vcc, 0
	v_add_f32_e32 v210, v235, v102
	s_cselect_b64 s[46:47], -1, 0
	s_cbranch_vccnz .LBB0_272

.LBB0_267:
	s_add_i32 s2, s96, 0x2000
	s_cmpk_lg_i32 s96, 0x4000
	s_cselect_b32 s24, s2, 0
	v_mfma_f32_32x32x16_bf16 v[112:127], v[96:99], v[184:187], v[80:95]
	v_add_f32_e32 v100, v144, v145
	v_add_f32_e32 v100, v146, v100
	v_add_f32_e32 v100, v147, v100
	s_lshl_b32 s2, s4, 1
	v_add_f32_e32 v100, v148, v100
	v_add_u32_e32 v229, s2, v233
	v_add_f32_e32 v96, v149, v100
	v_cvt_pk_bf16_f32 v188, v144, v145
	v_cvt_pk_bf16_f32 v189, v146, v147
	s_nop 0
	v_add_f32_e32 v96, v150, v96
	v_add_f32_e32 v96, v151, v96
	v_add_f32_e32 v96, v152, v96
	v_add_f32_e32 v144, v153, v96
	v_mfma_f32_32x32x16_bf16 v[96:111], v[200:203], v[184:187], v[80:95]
	v_cvt_pk_bf16_f32 v190, v148, v149
	v_cvt_pk_bf16_f32 v191, v150, v151
	v_mfma_f32_32x32x16_bf16 v[112:127], v[204:207], v[176:179], v[112:127]
	v_add_f32_e32 v144, v154, v144
	v_add_f32_e32 v144, v155, v144
	v_add_f32_e32 v144, v156, v144
	v_add_f32_e32 v144, v157, v144
	v_cvt_pk_bf16_f32 v180, v152, v153
	v_cvt_pk_bf16_f32 v181, v154, v155
	v_mfma_f32_32x32x16_bf16 v[96:111], v[196:199], v[176:179], v[96:111]
	v_add_f32_e32 v144, v158, v144
	v_add_f32_e32 v144, v159, v144
	v_add_f32_e32 v144, v128, v144
	v_add_f32_e32 v144, v129, v144
	v_cvt_pk_bf16_f32 v182, v156, v157
	v_cvt_pk_bf16_f32 v183, v158, v159
	v_mfma_f32_32x32x16_bf16 v[112:127], v[192:195], v[172:175], v[112:127]
	v_add_f32_e32 v144, v130, v144
	v_add_f32_e32 v144, v131, v144
	v_add_f32_e32 v144, v132, v144
	v_add_f32_e32 v144, v133, v144
	v_cvt_pk_bf16_f32 v168, v128, v129
	v_cvt_pk_bf16_f32 v169, v130, v131
	v_mfma_f32_32x32x16_bf16 v[96:111], v[10:13], v[172:175], v[96:111]
	v_add_f32_e32 v10, v134, v144
	v_add_f32_e32 v10, v135, v10
	v_add_f32_e32 v10, v136, v10
	v_add_f32_e32 v10, v137, v10
	v_cvt_pk_bf16_f32 v170, v132, v133
	v_cvt_pk_bf16_f32 v171, v134, v135
	v_mfma_f32_32x32x16_bf16 v[112:127], v[6:9], v[164:167], v[112:127]
	v_add_f32_e32 v6, v138, v10
	v_add_f32_e32 v6, v139, v6
	v_add_f32_e32 v6, v140, v6
	v_add_f32_e32 v6, v141, v6
	v_cvt_pk_bf16_f32 v160, v136, v137
	v_cvt_pk_bf16_f32 v161, v138, v139
	v_mfma_f32_32x32x16_bf16 v[96:111], v[2:5], v[164:167], v[96:111]
	v_add_f32_e32 v2, v142, v6
	v_add_f32_e32 v134, v143, v2
	v_cvt_pk_bf16_f32 v162, v140, v141
	v_cvt_pk_bf16_f32 v163, v142, v143
	ds_read_b64_tr_b16 v[128:129], v229 offset:24576
	ds_read_b64_tr_b16 v[130:131], v229 offset:25088
	ds_read_b64_tr_b16 v[10:11], v229 offset:28672
	ds_read_b64_tr_b16 v[12:13], v229 offset:29184
	ds_read_b64_tr_b16 v[6:7], v229 offset:32768
	ds_read_b64_tr_b16 v[8:9], v229 offset:33280
	ds_read_b64_tr_b16 v[2:3], v229 offset:36864
	ds_read_b64_tr_b16 v[4:5], v229 offset:37376
	s_mov_b64 s[2:3], 0xa0000
	v_lshl_add_u64 v[132:133], v[208:209], 0, s[2:3]
	s_add_i32 s2, s96, s22
	s_mov_b32 m0, s2
	s_nop 0
	global_load_lds_dwordx4 v[132:133], off
	s_mov_b64 s[2:3], 0xfe60000
	v_lshl_add_u64 v[132:133], v[14:15], 0, s[2:3]
	s_lshl_b32 s2, s24, 1
	s_add_i32 s4, s2, s23
	s_mov_b32 m0, s4
	s_nop 0
	global_load_lds_dwordx4 v[132:133], off
	s_mov_b64 s[2:3], 0xfe60080
	v_lshl_add_u64 v[14:15], v[14:15], 0, s[2:3]
	s_add_i32 s2, s4, 0x2000
	s_mov_b32 m0, s2
	s_nop 0
	global_load_lds_dwordx4 v[14:15], off
	v_max_f32_e32 v14, v112, v113
	v_max3_f32 v15, v114, v115, v97
	v_max3_f32 v14, v14, v96, v98
	v_max3_f32 v14, v14, v99, v116
	v_max3_f32 v15, v15, v118, v119
	v_max3_f32 v14, v14, v117, v100
	v_max3_f32 v15, v15, v102, v103
	v_max3_f32 v14, v14, v101, v120
	v_max3_f32 v15, v15, v122, v123
	v_max3_f32 v14, v14, v121, v104
	v_max3_f32 v15, v15, v106, v107
	v_max3_f32 v14, v14, v105, v124
	v_max3_f32 v15, v15, v126, v127
	v_max3_f32 v14, v14, v125, v108
	v_max3_f32 v15, v15, v110, v111
	v_max3_f32 v14, v14, v109, v15
	v_mov_b32_e32 v15, v14
	s_nop 1
	v_permlane32_swap_b32_e32 v14, v15
	v_max_f32_e32 v14, v14, v15
	v_cmp_lt_f32_e32 vcc, s11, v14
	s_cmp_lg_u64 vcc, 0
	v_add_f32_e32 v235, v210, v134
	s_cselect_b64 s[46:47], -1, 0
	s_cbranch_vccnz .LBB0_275

.LBB0_285:
	s_waitcnt lgkmcnt(7)
	v_mfma_f32_32x32x16_bf16 v[144:159], v[220:223], v[184:187], v[80:95]
	v_add_f32_e32 v2, v112, v113
	v_add_f32_e32 v2, v114, v2
	v_add_f32_e32 v2, v115, v2
	s_lshl_b32 s2, s96, 1
	v_add_f32_e32 v2, v116, v2
	v_add_u32_e32 v0, s2, v233
	v_add_f32_e32 v2, v117, v2
	v_cvt_pk_bf16_f32 v188, v112, v113
	v_cvt_pk_bf16_f32 v189, v114, v115
	s_waitcnt lgkmcnt(6)
	v_mfma_f32_32x32x16_bf16 v[128:143], v[216:219], v[184:187], v[80:95]
	v_add_f32_e32 v2, v118, v2
	v_add_f32_e32 v2, v119, v2
	v_add_f32_e32 v2, v120, v2
	v_add_f32_e32 v2, v121, v2
	v_cvt_pk_bf16_f32 v190, v116, v117
	v_cvt_pk_bf16_f32 v191, v118, v119
	s_waitcnt lgkmcnt(5)
	v_mfma_f32_32x32x16_bf16 v[144:159], v[212:215], v[176:179], v[144:159]
	v_add_f32_e32 v2, v122, v2
	v_add_f32_e32 v2, v123, v2
	v_add_f32_e32 v2, v124, v2
	v_add_f32_e32 v2, v125, v2
	v_cvt_pk_bf16_f32 v180, v120, v121
	v_cvt_pk_bf16_f32 v181, v122, v123
	s_waitcnt lgkmcnt(4)
	v_mfma_f32_32x32x16_bf16 v[128:143], v[208:211], v[176:179], v[128:143]
	v_add_f32_e32 v2, v126, v2
	v_add_f32_e32 v2, v127, v2
	v_add_f32_e32 v2, v96, v2
	v_add_f32_e32 v2, v97, v2
	v_cvt_pk_bf16_f32 v182, v124, v125
	v_cvt_pk_bf16_f32 v183, v126, v127
	s_waitcnt lgkmcnt(3)
	v_mfma_f32_32x32x16_bf16 v[144:159], v[204:207], v[172:175], v[144:159]
	v_add_f32_e32 v2, v98, v2
	v_add_f32_e32 v2, v99, v2
	v_add_f32_e32 v2, v100, v2
	v_add_f32_e32 v2, v101, v2
	v_cvt_pk_bf16_f32 v168, v96, v97
	v_cvt_pk_bf16_f32 v169, v98, v99
	s_waitcnt lgkmcnt(2)
	v_mfma_f32_32x32x16_bf16 v[128:143], v[200:203], v[172:175], v[128:143]
	v_add_f32_e32 v2, v102, v2
	v_add_f32_e32 v2, v103, v2
	v_add_f32_e32 v2, v104, v2
	v_add_f32_e32 v2, v105, v2
	v_cvt_pk_bf16_f32 v170, v100, v101
	v_cvt_pk_bf16_f32 v171, v102, v103
	s_waitcnt lgkmcnt(1)
	v_mfma_f32_32x32x16_bf16 v[144:159], v[196:199], v[164:167], v[144:159]
	v_add_f32_e32 v2, v106, v2
	v_add_f32_e32 v2, v107, v2
	v_add_f32_e32 v2, v108, v2
	v_add_f32_e32 v2, v109, v2
	v_cvt_pk_bf16_f32 v160, v104, v105
	v_cvt_pk_bf16_f32 v161, v106, v107
	s_waitcnt lgkmcnt(0)
	v_mfma_f32_32x32x16_bf16 v[128:143], v[192:195], v[164:167], v[128:143]
	v_add_f32_e32 v2, v110, v2
	v_add_f32_e32 v100, v111, v2
	v_cvt_pk_bf16_f32 v162, v108, v109
	v_cvt_pk_bf16_f32 v163, v110, v111
	ds_read_b64_tr_b16 v[96:97], v0 offset:24576
	ds_read_b64_tr_b16 v[98:99], v0 offset:25088
	ds_read_b64_tr_b16 v[10:11], v0 offset:28672
	ds_read_b64_tr_b16 v[12:13], v0 offset:29184
	ds_read_b64_tr_b16 v[6:7], v0 offset:32768
	ds_read_b64_tr_b16 v[8:9], v0 offset:33280
	ds_read_b64_tr_b16 v[2:3], v0 offset:36864
	ds_read_b64_tr_b16 v[4:5], v0 offset:37376
	s_add_i32 s2, s12, 1
	s_cmp_ge_u32 s2, s68
	s_cselect_b64 s[92:93], -1, 0
	s_and_b64 vcc, exec, s[92:93]
	v_lshl_add_u64 v[242:243], v[238:239], 0, s[94:95]
	s_cbranch_vccnz .LBB0_287
	v_lshl_add_u64 v[102:103], v[242:243], 0, s[72:73]
	s_add_i32 s2, s24, s22
	s_mov_b32 m0, s2
	s_nop 0
	global_load_lds_dwordx4 v[102:103], off

.LBB0_289:
	v_add_f32_e32 v228, v235, v100
	v_max_f32_e32 v100, v144, v145
	v_max3_f32 v101, v146, v147, v129
	v_max3_f32 v100, v100, v128, v130
	v_max3_f32 v100, v100, v131, v148
	v_max3_f32 v101, v101, v150, v151
	v_max3_f32 v100, v100, v149, v132
	v_max3_f32 v101, v101, v134, v135
	v_max3_f32 v100, v100, v133, v152
	v_max3_f32 v101, v101, v154, v155
	v_max3_f32 v100, v100, v153, v136
	v_max3_f32 v101, v101, v138, v139
	v_max3_f32 v100, v100, v137, v156
	v_max3_f32 v101, v101, v158, v159
	v_max3_f32 v100, v100, v157, v140
	v_max3_f32 v101, v101, v142, v143
	v_max3_f32 v100, v100, v141, v101
	v_mov_b32_e32 v101, v100
	s_nop 1
	v_permlane32_swap_b32_e32 v100, v101
	v_max_f32_e32 v100, v100, v101
	v_cmp_lt_f32_e32 vcc, s11, v100
	s_cmp_lg_u64 vcc, 0
	s_cselect_b64 s[40:41], -1, 0
	s_cbranch_vccnz .LBB0_327

.LBB0_294:
	v_mfma_f32_32x32x16_bf16 v[112:127], v[220:223], v[184:187], v[80:95]
	v_add_f32_e32 v2, v144, v145
	v_add_f32_e32 v2, v146, v2
	v_add_f32_e32 v2, v147, v2
	s_lshl_b32 s2, s24, 1
	v_add_f32_e32 v2, v148, v2
	v_add_u32_e32 v229, s2, v233
	v_add_f32_e32 v2, v149, v2
	v_cvt_pk_bf16_f32 v188, v144, v145
	v_cvt_pk_bf16_f32 v189, v146, v147
	v_mfma_f32_32x32x16_bf16 v[96:111], v[216:219], v[184:187], v[80:95]
	v_add_f32_e32 v2, v150, v2
	v_add_f32_e32 v2, v151, v2
	v_add_f32_e32 v2, v152, v2
	v_add_f32_e32 v2, v153, v2
	v_cvt_pk_bf16_f32 v190, v148, v149
	v_cvt_pk_bf16_f32 v191, v150, v151
	v_mfma_f32_32x32x16_bf16 v[112:127], v[212:215], v[176:179], v[112:127]
	v_add_f32_e32 v2, v154, v2
	v_add_f32_e32 v2, v155, v2
	v_add_f32_e32 v2, v156, v2
	v_add_f32_e32 v2, v157, v2
	v_cvt_pk_bf16_f32 v180, v152, v153
	v_cvt_pk_bf16_f32 v181, v154, v155
	v_mfma_f32_32x32x16_bf16 v[96:111], v[208:211], v[176:179], v[96:111]
	v_add_f32_e32 v2, v158, v2
	v_add_f32_e32 v2, v159, v2
	v_add_f32_e32 v2, v128, v2
	v_add_f32_e32 v2, v129, v2
	v_cvt_pk_bf16_f32 v182, v156, v157
	v_cvt_pk_bf16_f32 v183, v158, v159
	v_mfma_f32_32x32x16_bf16 v[112:127], v[204:207], v[172:175], v[112:127]
	v_add_f32_e32 v2, v130, v2
	v_add_f32_e32 v2, v131, v2
	v_add_f32_e32 v2, v132, v2
	v_add_f32_e32 v2, v133, v2
	v_cvt_pk_bf16_f32 v168, v128, v129
	v_cvt_pk_bf16_f32 v169, v130, v131
	v_mfma_f32_32x32x16_bf16 v[96:111], v[200:203], v[172:175], v[96:111]
	v_add_f32_e32 v2, v134, v2
	v_add_f32_e32 v2, v135, v2
	v_add_f32_e32 v2, v136, v2
	v_add_f32_e32 v2, v137, v2
	v_cvt_pk_bf16_f32 v170, v132, v133
	v_cvt_pk_bf16_f32 v171, v134, v135
	v_mfma_f32_32x32x16_bf16 v[112:127], v[196:199], v[164:167], v[112:127]
	v_add_f32_e32 v2, v138, v2
	v_add_f32_e32 v2, v139, v2
	v_add_f32_e32 v2, v140, v2
	v_add_f32_e32 v2, v141, v2
	v_cvt_pk_bf16_f32 v160, v136, v137
	v_cvt_pk_bf16_f32 v161, v138, v139
	v_mfma_f32_32x32x16_bf16 v[96:111], v[192:195], v[164:167], v[96:111]
	v_add_f32_e32 v2, v142, v2
	v_add_f32_e32 v132, v143, v2
	v_cvt_pk_bf16_f32 v162, v140, v141
	v_cvt_pk_bf16_f32 v163, v142, v143
	ds_read_b64_tr_b16 v[128:129], v229 offset:24576
	ds_read_b64_tr_b16 v[130:131], v229 offset:25088
	ds_read_b64_tr_b16 v[10:11], v229 offset:28672
	ds_read_b64_tr_b16 v[12:13], v229 offset:29184
	ds_read_b64_tr_b16 v[6:7], v229 offset:32768
	ds_read_b64_tr_b16 v[8:9], v229 offset:33280
	ds_read_b64_tr_b16 v[2:3], v229 offset:36864
	ds_read_b64_tr_b16 v[4:5], v229 offset:37376
	s_add_i32 s2, s12, 2
	s_cmp_ge_u32 s2, s68
	s_cselect_b64 s[96:97], -1, 0
	s_and_b64 vcc, exec, s[96:97]
	s_cbranch_vccnz .LBB0_296
	v_lshl_add_u64 v[134:135], v[242:243], 0, s[74:75]
	s_add_i32 s3, s25, s22
	s_mov_b32 m0, s3
	s_nop 0
	global_load_lds_dwordx4 v[134:135], off

.LBB0_300:
	v_add_f32_e32 v235, v228, v132
	v_max_f32_e32 v132, v112, v113
	v_max3_f32 v133, v114, v115, v97
	v_max3_f32 v132, v132, v96, v98
	v_max3_f32 v132, v132, v99, v116
	v_max3_f32 v133, v133, v118, v119
	v_max3_f32 v132, v132, v117, v100
	v_max3_f32 v133, v133, v102, v103
	v_max3_f32 v132, v132, v101, v120
	v_max3_f32 v133, v133, v122, v123
	v_max3_f32 v132, v132, v121, v104
	v_max3_f32 v133, v133, v106, v107
	v_max3_f32 v132, v132, v105, v124
	v_max3_f32 v133, v133, v126, v127
	v_max3_f32 v132, v132, v125, v108
	v_max3_f32 v133, v133, v110, v111
	v_max3_f32 v132, v132, v109, v133
	v_mov_b32_e32 v133, v132
	s_nop 1
	v_permlane32_swap_b32_e32 v132, v133
	v_max_f32_e32 v132, v132, v133
	v_cmp_lt_f32_e32 vcc, s11, v132
	s_cmp_lg_u64 vcc, 0
	s_cselect_b64 s[46:47], -1, 0
	s_cbranch_vccnz .LBB0_330

; __device__ __forceinline__ void cmask(f32x16&p0,f32x16&p1,int jb,int qrel,int hi){
;   const float NEG=-INFINITY; (void)hi;
;   #pragma unroll
;   for(int r=0;r<16;++r){ if(jb>(qrel>>6)){p0[r]=NEG; p1[r]=NEG;} }
; }
.LBB0_335:
	v_add_f32_e32 v0, v112, v113
	v_add_f32_e32 v0, v114, v0
	v_add_f32_e32 v0, v115, v0
	v_add_f32_e32 v0, v116, v0
	v_add_u32_e32 v14, s4, v233
	v_add_f32_e32 v0, v117, v0
	v_cvt_pk_bf16_f32 v188, v112, v113
	v_cvt_pk_bf16_f32 v189, v114, v115
	s_waitcnt lgkmcnt(7)
	v_mfma_f32_32x32x16_bf16 v[128:143], v[220:223], v[184:187], v[80:95]
	s_waitcnt lgkmcnt(6)
	v_mfma_f32_32x32x16_bf16 v[80:95], v[216:219], v[184:187], v[80:95]
	v_add_f32_e32 v0, v118, v0
	v_add_f32_e32 v0, v119, v0
	v_add_f32_e32 v0, v120, v0
	v_add_f32_e32 v0, v121, v0
	v_cvt_pk_bf16_f32 v190, v116, v117
	v_cvt_pk_bf16_f32 v191, v118, v119
	s_nop 0
	v_add_f32_e32 v0, v122, v0
	v_add_f32_e32 v0, v123, v0
	v_add_f32_e32 v0, v124, v0
	v_add_f32_e32 v0, v125, v0
	v_cvt_pk_bf16_f32 v180, v120, v121
	v_cvt_pk_bf16_f32 v181, v122, v123
	s_waitcnt lgkmcnt(5)
	v_mfma_f32_32x32x16_bf16 v[128:143], v[212:215], v[176:179], v[128:143]
	s_waitcnt lgkmcnt(4)
	v_mfma_f32_32x32x16_bf16 v[80:95], v[208:211], v[176:179], v[80:95]
	v_add_f32_e32 v0, v126, v0
	v_add_f32_e32 v0, v127, v0
	v_add_f32_e32 v0, v96, v0
	v_add_f32_e32 v0, v97, v0
	v_cvt_pk_bf16_f32 v182, v124, v125
	v_cvt_pk_bf16_f32 v183, v126, v127
	s_nop 0
	v_add_f32_e32 v0, v98, v0
	v_add_f32_e32 v0, v99, v0
	v_add_f32_e32 v0, v100, v0
	v_add_f32_e32 v0, v101, v0
	v_cvt_pk_bf16_f32 v168, v96, v97
	v_cvt_pk_bf16_f32 v169, v98, v99
	s_waitcnt lgkmcnt(3)
	v_mfma_f32_32x32x16_bf16 v[128:143], v[204:207], v[172:175], v[128:143]
	s_waitcnt lgkmcnt(2)
	v_mfma_f32_32x32x16_bf16 v[80:95], v[200:203], v[172:175], v[80:95]
	v_add_f32_e32 v0, v102, v0
	v_add_f32_e32 v0, v103, v0
	v_add_f32_e32 v0, v104, v0
	v_add_f32_e32 v0, v105, v0
	v_cvt_pk_bf16_f32 v170, v100, v101
	v_cvt_pk_bf16_f32 v171, v102, v103
	s_nop 0
	v_add_f32_e32 v0, v106, v0
	v_add_f32_e32 v0, v107, v0
	v_add_f32_e32 v0, v108, v0
	v_add_f32_e32 v0, v109, v0
	v_cvt_pk_bf16_f32 v160, v104, v105
	v_cvt_pk_bf16_f32 v161, v106, v107
	s_waitcnt lgkmcnt(1)
	v_mfma_f32_32x32x16_bf16 v[128:143], v[196:199], v[164:167], v[128:143]
	s_waitcnt lgkmcnt(0)
	v_mfma_f32_32x32x16_bf16 v[80:95], v[192:195], v[164:167], v[80:95]
	v_add_f32_e32 v0, v110, v0
	v_add_f32_e32 v0, v111, v0
	v_cvt_pk_bf16_f32 v162, v108, v109
	v_cvt_pk_bf16_f32 v163, v110, v111
	ds_read_b64_tr_b16 v[144:145], v14 offset:24576
	ds_read_b64_tr_b16 v[146:147], v14 offset:25088
	ds_read_b64_tr_b16 v[10:11], v14 offset:28672
	ds_read_b64_tr_b16 v[12:13], v14 offset:29184
	ds_read_b64_tr_b16 v[6:7], v14 offset:32768
	ds_read_b64_tr_b16 v[8:9], v14 offset:33280
	ds_read_b64_tr_b16 v[2:3], v14 offset:36864
	ds_read_b64_tr_b16 v[4:5], v14 offset:37376
	s_cmpk_lt_i32 s33, 0x180
	s_cselect_b64 vcc, -1, 0
	v_cndmask_b32_e32 v97, v129, v248, vcc
	v_cndmask_b32_e32 v96, v128, v248, vcc
	v_max_f32_e32 v15, v97, v97
	v_max_f32_e32 v112, v96, v96
	v_cndmask_b32_e32 v99, v131, v248, vcc
	v_cndmask_b32_e32 v98, v130, v248, vcc
	v_cndmask_b32_e32 v82, v82, v248, vcc
	v_cndmask_b32_e32 v81, v81, v248, vcc
	v_cndmask_b32_e32 v80, v80, v248, vcc
	v_max_f32_e32 v15, v112, v15
	v_cndmask_b32_e32 v103, v135, v248, vcc
	v_cndmask_b32_e32 v102, v134, v248, vcc
	v_cndmask_b32_e32 v100, v132, v248, vcc
	v_cndmask_b32_e32 v83, v83, v248, vcc
	v_max3_f32 v112, v98, v99, v81
	v_max3_f32 v15, v15, v80, v82
	v_cndmask_b32_e32 v101, v133, v248, vcc
	v_cndmask_b32_e32 v87, v87, v248, vcc
	v_cndmask_b32_e32 v86, v86, v248, vcc
	v_cndmask_b32_e32 v84, v84, v248, vcc
	v_max3_f32 v15, v15, v83, v100
	v_max3_f32 v112, v112, v102, v103
	v_cndmask_b32_e32 v107, v139, v248, vcc
	v_cndmask_b32_e32 v106, v138, v248, vcc
	v_cndmask_b32_e32 v104, v136, v248, vcc
	v_cndmask_b32_e32 v85, v85, v248, vcc
	v_max3_f32 v15, v15, v101, v84
	v_max3_f32 v112, v112, v86, v87
	v_cndmask_b32_e32 v105, v137, v248, vcc
	v_cndmask_b32_e32 v91, v91, v248, vcc
	v_cndmask_b32_e32 v90, v90, v248, vcc
	v_cndmask_b32_e32 v88, v88, v248, vcc
	v_max3_f32 v15, v15, v85, v104
	v_max3_f32 v112, v112, v106, v107
	v_cndmask_b32_e32 v111, v143, v248, vcc
	v_cndmask_b32_e32 v110, v142, v248, vcc
	v_cndmask_b32_e32 v108, v140, v248, vcc
	v_cndmask_b32_e32 v89, v89, v248, vcc
	v_max3_f32 v15, v15, v105, v88
	v_max3_f32 v112, v112, v90, v91
	v_cndmask_b32_e32 v109, v141, v248, vcc
	v_cndmask_b32_e32 v95, v95, v248, vcc
	v_cndmask_b32_e32 v94, v94, v248, vcc
	v_cndmask_b32_e32 v92, v92, v248, vcc
	v_max3_f32 v15, v15, v89, v108
	v_max3_f32 v112, v112, v110, v111
	v_cndmask_b32_e32 v93, v93, v248, vcc
	v_max3_f32 v15, v15, v109, v92
	v_max3_f32 v112, v112, v94, v95
	v_max3_f32 v15, v15, v93, v112
	v_mov_b32_e32 v112, v15
	s_nop 1
	v_permlane32_swap_b32_e32 v15, v112
	v_max_f32_e32 v15, v15, v112
	v_cmp_lt_f32_e32 vcc, s11, v15
	s_cmp_lg_u64 vcc, 0
	v_add_f32_e32 v0, v235, v0
	s_cselect_b64 s[38:39], -1, 0
	s_cbranch_vccnz .LBB0_340
